# static s_setprio 1 for wr=0 waves during tile transition (epilogue+header+READ), reset at first MMA block / phase exit
# baseline (speedup 1.0000x reference)
; #define G_WAIT_V(n) asm volatile("s_waitcnt vmcnt(" #n ")" ::: "memory")
; #define G_BAR __builtin_amdgcn_s_barrier()
; template <int MODE  , class Epi, class Sched>
; __device__ __forceinline__ void gemm_phase(LAS unsigned char* lds, const GemmDesc g, const Sched& S, const Epi& E) {
;     ...
;             G_WAIT_V(6); G_BAR; G_MMA(1, 1, At, B1); G_BAR;
;         }
;         if constexpr (MODE == 1) asm volatile("s_nop 15\n\ts_nop 15" ::: "memory");
;         const bool zero = E(acc, cur, wr, wc, fr, fq);
;         if (!has_next) break;
.Lkdone_p1c:
	s_cmpk_gt_u32 s31, 0xff
	s_cselect_b32 s101, 1, 0
	s_cbranch_scc1 .Lkepi_p1c
	s_barrier
	s_setprio 1

; #define G_WAIT_V(n) asm volatile("s_waitcnt vmcnt(" #n ")" ::: "memory")
; #define G_BAR __builtin_amdgcn_s_barrier()
; template <int MODE  , class Epi, class Sched>
; __device__ __forceinline__ void gemm_phase(LAS unsigned char* lds, const GemmDesc g, const Sched& S, const Epi& E) {
;     ...
;     G_WAIT_V(0);
;     if (wr == 0) G_BAR;
;     G_BAR;
.Lnodx_p1c:
	s_setprio 0
	s_waitcnt vmcnt(0)
	s_cmpk_gt_u32 s31, 0xff
	s_cbranch_scc1 .LBB0_636
	s_barrier

; #define G_WAIT_V(n) asm volatile("s_waitcnt vmcnt(" #n ")" ::: "memory")
; #define G_BAR __builtin_amdgcn_s_barrier()
; template <int MODE  , class Epi, class Sched>
; __device__ __forceinline__ void gemm_phase(LAS unsigned char* lds, const GemmDesc g, const Sched& S, const Epi& E) {
;     ...
;             G_WAIT_V(6); G_BAR; G_MMA(1, 1, At, B1); G_BAR;
;         }
;         if constexpr (MODE == 1) asm volatile("s_nop 15\n\ts_nop 15" ::: "memory");
;         const bool zero = E(acc, cur, wr, wc, fr, fq);
;         if (!has_next) break;
.Lkdone_sa:
	s_cmpk_gt_u32 s50, 0xff
	s_cselect_b32 s101, 1, 0
	s_cbranch_scc1 .Lkepi_sa
	s_barrier
	s_setprio 1

; #define G_WAIT_V(n) asm volatile("s_waitcnt vmcnt(" #n ")" ::: "memory")
; #define G_BAR __builtin_amdgcn_s_barrier()
; template <int MODE  , class Epi, class Sched>
; __device__ __forceinline__ void gemm_phase(LAS unsigned char* lds, const GemmDesc g, const Sched& S, const Epi& E) {
;     ...
;     G_WAIT_V(0);
;     if (wr == 0) G_BAR;
;     G_BAR;
.Lnodx_sa:
	s_setprio 0
	s_waitcnt vmcnt(0)
	s_cmpk_gt_u32 s50, 0xff
	s_cbranch_scc1 .LBB0_823
	s_barrier

; #define G_WAIT_V(n) asm volatile("s_waitcnt vmcnt(" #n ")" ::: "memory")
; #define G_BAR __builtin_amdgcn_s_barrier()
; template <int MODE  , class Epi, class Sched>
; __device__ __forceinline__ void gemm_phase(LAS unsigned char* lds, const GemmDesc g, const Sched& S, const Epi& E) {
;     ...
;             G_WAIT_V(6); G_BAR; G_MMA(1, 1, At, B1); G_BAR;
;         }
;         if constexpr (MODE == 1) asm volatile("s_nop 15\n\ts_nop 15" ::: "memory");
;         const bool zero = E(acc, cur, wr, wc, fr, fq);
;         if (!has_next) break;
.Lkdone_sb:
	s_cmpk_gt_u32 s48, 0xff
	s_cselect_b32 s101, 1, 0
	s_cbranch_scc1 .Lkepi_sb
	s_barrier
	s_setprio 1

; #define G_WAIT_V(n) asm volatile("s_waitcnt vmcnt(" #n ")" ::: "memory")
; #define G_BAR __builtin_amdgcn_s_barrier()
; template <int MODE  , class Epi, class Sched>
; __device__ __forceinline__ void gemm_phase(LAS unsigned char* lds, const GemmDesc g, const Sched& S, const Epi& E) {
;     ...
;     G_WAIT_V(0);
;     if (wr == 0) G_BAR;
;     G_BAR;
.Lnodx_sb:
	s_setprio 0
	s_waitcnt vmcnt(0)
	s_cmpk_gt_u32 s48, 0xff
	s_cbranch_scc1 .LBB0_913
	s_barrier

; #define G_WAIT_V(n) asm volatile("s_waitcnt vmcnt(" #n ")" ::: "memory")
; #define G_BAR __builtin_amdgcn_s_barrier()
; template <int MODE  , class Epi, class Sched>
; __device__ __forceinline__ void gemm_phase(LAS unsigned char* lds, const GemmDesc g, const Sched& S, const Epi& E) {
;     ...
;             G_WAIT_V(6); G_BAR; G_MMA(1, 1, At, B1); G_BAR;
;         }
;         if constexpr (MODE == 1) asm volatile("s_nop 15\n\ts_nop 15" ::: "memory");
;         const bool zero = E(acc, cur, wr, wc, fr, fq);
;         if (!has_next) break;
.Lkdone_sc:
	s_cmpk_gt_u32 s9, 0xff
	s_cselect_b32 s101, 1, 0
	s_cbranch_scc1 .Lkepi_sc
	s_barrier
	s_setprio 1

; #define G_WAIT_V(n) asm volatile("s_waitcnt vmcnt(" #n ")" ::: "memory")
; #define G_BAR __builtin_amdgcn_s_barrier()
; template <int MODE  , class Epi, class Sched>
; __device__ __forceinline__ void gemm_phase(LAS unsigned char* lds, const GemmDesc g, const Sched& S, const Epi& E) {
;     ...
;     G_WAIT_V(0);
;     if (wr == 0) G_BAR;
;     G_BAR;
.Lnodx_sc:
	s_setprio 0
	s_waitcnt vmcnt(0)
	s_cmpk_gt_u32 s9, 0xff
	s_cbranch_scc1 .LBB0_995
	s_barrier

; #define G_WAIT_V(n) asm volatile("s_waitcnt vmcnt(" #n ")" ::: "memory")
; #define G_BAR __builtin_amdgcn_s_barrier()
; template <int MODE  , class Epi, class Sched>
; __device__ __forceinline__ void gemm_phase(LAS unsigned char* lds, const GemmDesc g, const Sched& S, const Epi& E) {
;     ...
;             G_WAIT_V(6); G_BAR; G_MMA(1, 1, At, B1); G_BAR;
;         }
;         if constexpr (MODE == 1) asm volatile("s_nop 15\n\ts_nop 15" ::: "memory");
;         const bool zero = E(acc, cur, wr, wc, fr, fq);
;         if (!has_next) break;
.Lkdone_s1a:
	s_cmpk_gt_u32 s54, 0xff
	s_cselect_b32 s101, 1, 0
	s_cbranch_scc1 .Lkepi_s1a
	s_barrier
	s_setprio 1

; #define G_WAIT_V(n) asm volatile("s_waitcnt vmcnt(" #n ")" ::: "memory")
; #define G_BAR __builtin_amdgcn_s_barrier()
; template <int MODE  , class Epi, class Sched>
; __device__ __forceinline__ void gemm_phase(LAS unsigned char* lds, const GemmDesc g, const Sched& S, const Epi& E) {
;     ...
;     G_WAIT_V(0);
;     if (wr == 0) G_BAR;
;     G_BAR;
.Lnodx_s1a:
	s_setprio 0
	s_waitcnt vmcnt(0)
	s_cmpk_gt_u32 s54, 0xff
	s_cbranch_scc1 .LBB0_1134
	s_barrier
